# k7 plus pv-wave P-fragment reads issued up front with counted lgkmcnt waits (row groups 0 and 2) in mixer B
# baseline (speedup 1.0000x reference)
; __device__ __forceinline__ void attn_b2_unit(int b, int h, int qk, int jlo, const bf16_t* __restrict__ P, bf16_t* __restrict__ mix, const float* __restrict__ subg, float lam,
;                                              float* __restrict__ o0s, char* lds) {
;     ...
;                             const char* pp = lds + B2_P + (pb * 4 + rg) * 4096 + lane * 16;
;                             const bf16x8 pa0 = *(const bf16x8*)(pp), pa1 = *(const bf16x8*)(pp + 1024), pa2 = *(const bf16x8*)(pp + 2048), pa3 = *(const bf16x8*)(pp + 3072);
;                             o[2 * rg] = __builtin_amdgcn_mfma_f32_32x32x16_bf16(pa0, vf[0][0], o[2 * rg], 0, 0, 0); o[2 * rg + 1] = __builtin_amdgcn_mfma_f32_32x32x16_bf16(pa0, vf[1][0], o[2 * rg + 1], 0, 0, 0);
;                             o[2 * rg] = __builtin_amdgcn_mfma_f32_32x32x16_bf16(pa1, vf[0][1], o[2 * rg], 0, 0, 0); o[2 * rg + 1] = __builtin_amdgcn_mfma_f32_32x32x16_bf16(pa1, vf[1][1], o[2 * rg + 1], 0, 0, 0);
;                             o[2 * rg] = __builtin_amdgcn_mfma_f32_32x32x16_bf16(pa2, vf[0][2], o[2 * rg], 0, 0, 0); o[2 * rg + 1] = __builtin_amdgcn_mfma_f32_32x32x16_bf16(pa2, vf[1][2], o[2 * rg + 1], 0, 0, 0);
;                             o[2 * rg] = __builtin_amdgcn_mfma_f32_32x32x16_bf16(pa3, vf[0][3], o[2 * rg], 0, 0, 0); o[2 * rg + 1] = __builtin_amdgcn_mfma_f32_32x32x16_bf16(pa3, vf[1][3], o[2 * rg + 1], 0, 0, 0);
.LBB0_372:
	v_lshl_add_u32 v1, s46, 14, v168
	ds_read_b128 v[212:215], v1
	ds_read_b128 v[216:219], v1 offset:1024
	ds_read_b128 v[220:223], v1 offset:2048
	ds_read_b128 v[224:227], v1 offset:3072
	s_waitcnt lgkmcnt(3)
	v_mfma_f32_32x32x16_bf16 v[128:143], v[212:215], v[152:155], v[128:143]
	v_mfma_f32_32x32x16_bf16 v[112:127], v[212:215], v[160:163], v[112:127]
	s_waitcnt lgkmcnt(2)
	v_mfma_f32_32x32x16_bf16 v[128:143], v[216:219], v[148:151], v[128:143]
	v_mfma_f32_32x32x16_bf16 v[112:127], v[216:219], v[156:159], v[112:127]
	s_waitcnt lgkmcnt(1)
	v_mfma_f32_32x32x16_bf16 v[128:143], v[220:223], v[6:9], v[128:143]
	v_mfma_f32_32x32x16_bf16 v[112:127], v[220:223], v[144:147], v[112:127]
	s_waitcnt lgkmcnt(0)
	v_mfma_f32_32x32x16_bf16 v[128:143], v[224:227], v[2:5], v[128:143]
	v_mfma_f32_32x32x16_bf16 v[112:127], v[224:227], v[10:13], v[112:127]

; __device__ __forceinline__ void attn_b2_unit(int b, int h, int qk, int jlo, const bf16_t* __restrict__ P, bf16_t* __restrict__ mix, const float* __restrict__ subg, float lam,
;                                              float* __restrict__ o0s, char* lds) {
;     ...
;                             const float* al = (const float*)(lds + B2_A + ((pb * 4 + rg) * 32) * 4);
;                             const float amine = al[r32];
;                             if (__any(amine < 1.f)) { const float* alh = al + 4 * hi;
; #pragma unroll
;                                 for (int r = 0; r < 16; ++r) { const float a = alh[(r & 3) + 8 * (r >> 2)]; o[2 * rg][r] *= a; o[2 * rg + 1][r] *= a; }
;                             }
;                             const char* pp = lds + B2_P + (pb * 4 + rg) * 4096 + lane * 16;
;                             const bf16x8 pa0 = *(const bf16x8*)(pp), pa1 = *(const bf16x8*)(pp + 1024), pa2 = *(const bf16x8*)(pp + 2048), pa3 = *(const bf16x8*)(pp + 3072);
;                             o[2 * rg] = __builtin_amdgcn_mfma_f32_32x32x16_bf16(pa0, vf[0][0], o[2 * rg], 0, 0, 0); o[2 * rg + 1] = __builtin_amdgcn_mfma_f32_32x32x16_bf16(pa0, vf[1][0], o[2 * rg + 1], 0, 0, 0);
;                             o[2 * rg] = __builtin_amdgcn_mfma_f32_32x32x16_bf16(pa1, vf[0][1], o[2 * rg], 0, 0, 0); o[2 * rg + 1] = __builtin_amdgcn_mfma_f32_32x32x16_bf16(pa1, vf[1][1], o[2 * rg + 1], 0, 0, 0);
;                             o[2 * rg] = __builtin_amdgcn_mfma_f32_32x32x16_bf16(pa2, vf[0][2], o[2 * rg], 0, 0, 0); o[2 * rg + 1] = __builtin_amdgcn_mfma_f32_32x32x16_bf16(pa2, vf[1][2], o[2 * rg + 1], 0, 0, 0);
;                             o[2 * rg] = __builtin_amdgcn_mfma_f32_32x32x16_bf16(pa3, vf[0][3], o[2 * rg], 0, 0, 0); o[2 * rg + 1] = __builtin_amdgcn_mfma_f32_32x32x16_bf16(pa3, vf[1][3], o[2 * rg + 1], 0, 0, 0);
.LBB0_379:
	v_lshl_add_u32 v1, s2, 12, v168
	ds_read_b128 v[212:215], v1
	ds_read_b128 v[216:219], v1 offset:1024
	ds_read_b128 v[220:223], v1 offset:2048
	ds_read_b128 v[224:227], v1 offset:3072
	s_or_b32 s2, s48, 3
	s_lshl_b32 s3, s2, 7
	s_add_i32 s3, s3, 0
	s_add_i32 s3, s3, 0x20000
	v_lshl_add_u32 v1, v165, 2, s3
	ds_read_b32 v1, v1
	s_waitcnt lgkmcnt(4)
	v_mfma_f32_32x32x16_bf16 v[64:79], v[212:215], v[152:155], v[64:79]
	v_mfma_f32_32x32x16_bf16 v[48:63], v[212:215], v[160:163], v[48:63]
	s_waitcnt lgkmcnt(3)
	v_mfma_f32_32x32x16_bf16 v[64:79], v[216:219], v[148:151], v[64:79]
	v_mfma_f32_32x32x16_bf16 v[48:63], v[216:219], v[156:159], v[48:63]
	s_waitcnt lgkmcnt(2)
	v_mfma_f32_32x32x16_bf16 v[64:79], v[220:223], v[6:9], v[64:79]
	v_mfma_f32_32x32x16_bf16 v[48:63], v[220:223], v[144:147], v[48:63]
	s_waitcnt lgkmcnt(0)
	v_cmp_gt_f32_e32 vcc, 1.0, v1
	v_mfma_f32_32x32x16_bf16 v[64:79], v[224:227], v[2:5], v[64:79]
	v_mfma_f32_32x32x16_bf16 v[48:63], v[224:227], v[10:13], v[48:63]
	s_cbranch_vccz .LBB0_381
	v_add_u32_e32 v1, s3, v182
	ds_read_b128 v[212:215], v1 offset:96
	ds_read_b128 v[216:219], v1 offset:64
	ds_read_b128 v[220:223], v1 offset:32
	ds_read_b128 v[224:227], v1
	s_waitcnt lgkmcnt(0)
	v_pk_mul_f32 v[44:45], v[44:45], v[212:213]
	v_pk_mul_f32 v[40:41], v[40:41], v[216:217]
	v_pk_mul_f32 v[36:37], v[36:37], v[220:221]
	v_pk_mul_f32 v[46:47], v[46:47], v[214:215]
	v_pk_mul_f32 v[42:43], v[42:43], v[218:219]
	v_pk_mul_f32 v[38:39], v[38:39], v[222:223]
	v_pk_mul_f32 v[34:35], v[34:35], v[226:227]
	v_pk_mul_f32 v[32:33], v[32:33], v[224:225]
	v_pk_mul_f32 v[28:29], v[28:29], v[212:213]
	v_pk_mul_f32 v[24:25], v[24:25], v[216:217]
	v_pk_mul_f32 v[20:21], v[20:21], v[220:221]
	v_pk_mul_f32 v[30:31], v[30:31], v[214:215]
	v_pk_mul_f32 v[26:27], v[26:27], v[218:219]
	v_pk_mul_f32 v[22:23], v[22:23], v[222:223]
	v_pk_mul_f32 v[18:19], v[18:19], v[226:227]
	v_pk_mul_f32 v[16:17], v[16:17], v[224:225]
